# v057 + attention tile-issue blocks: m0 save/restore around each LDS-DMA piece removed (8 SALU per iteration; m0 has no other consumer)
# baseline (speedup 1.0000x reference)
; #define LAS __attribute__((address_space(3)))
; DI unsigned lds_addr(const LAS void* p) { return (unsigned)__builtin_amdgcn_readfirstlane((int)(unsigned)(size_t)p); }
; DI void load_tile(LAS unsigned char* buf, const bf16* Kg, const bf16* Vg, int kv0, int wave, int lane) {
; #pragma unroll
;     for (int i = 0; i < 2; ++i) { const int c = 2 * wave + i;
;         glds16(Kg + (size_t)(kv0 + lane) * 128 + c * 8, lds_addr(buf + c * 1024)); }
; #pragma unroll
;     for (int i = 0; i < 2; ++i) { const int pc = 2 * wave + i;
;         glds16(Vg + (size_t)(kv0 + 16 * (pc & 3) + (lane >> 2)) * 128 + (pc >> 2) * 32 + (lane & 3) * 8, lds_addr(buf + KT + (pc >> 2) * 4096 + (pc & 3) * 1024)); }
; }
; DI void attn_unit(Ctx A_, LAS unsigned char* lds, int b, int h, int qb, float lam, int wave, int lane) {
;     ...
;         asm volatile("s_waitcnt vmcnt(0) lgkmcnt(0)" ::: "memory");
;         __builtin_amdgcn_s_barrier(); asm volatile("" ::: "memory");
;         if (t + 2 < NT) load_tile(lds + ((t + 2) & 3) * BUF, Kg, Vg, (t + 2) * 64, wave, lane);
.LBB0_872:
	s_waitcnt vmcnt(0) lgkmcnt(0)
	s_barrier
	s_cmp_ge_u32 s67, s65
	s_cbranch_scc1 .LBB0_874
	s_add_i32 s4, s66, 0x10000
	s_and_b32 s4, s4, 0x18000
	s_add_i32 s4, s4, 0
	s_add_i32 s5, s4, s33
	v_mov_b64_e32 v[82:83], v[202:203]
	s_mov_b32 m0, s5
	s_nop 0
	global_load_lds_dwordx4 v[82:83], off
	s_add_i32 s5, s4, s38
	s_add_i32 s4, s4, s30
	v_lshl_add_u64 v[82:83], v[202:203], 0, v[252:253]
	s_mov_b32 m0, s5
	s_nop 0
	global_load_lds_dwordx4 v[82:83], off
	s_add_i32 s5, s4, s34
	s_addk_i32 s5, 0x4000
	s_mov_b32 m0, s5
	s_nop 0
	global_load_lds_dwordx4 v[200:201], off
	s_add_i32 s4, s4, s43
	s_addk_i32 s4, 0x4000
	s_mov_b32 m0, s4
	s_nop 0
	global_load_lds_dwordx4 v[198:199], off
